# FFN-up epilogue: hoist the 8 per-row rs loads, counted vmcnt(7) so iterations do not wait for the previous store
# speedup vs baseline: 1.0278x; 1.0035x over previous
.LBB0_229:
	s_min_i32 s13, s33, 64
	s_lshr_b32 s13, s13, 4
	s_mul_i32 s20, s13, 0x1600
	s_ashr_i32 s21, s20, 31
	s_lshl_b64 s[20:21], s[20:21], 2
	s_add_u32 s13, s37, s20
	s_addc_u32 s15, s38, s21
	s_lshl_b32 s20, s43, 8
	s_ashr_i32 s21, s20, 31
	s_lshl_b64 s[20:21], s[20:21], 2
	s_add_u32 s13, s13, s20
	s_addc_u32 s15, s15, s21
	s_add_u32 s20, s13, s42
	s_addc_u32 s21, s15, 0
	s_lshl_b32 s13, s33, 8
	v_add_u32_e32 v160, s13, v1
	v_ashrrev_i32_e32 v161, 31, v160
	v_lshl_add_u64 v[172:173], v[160:161], 2, s[6:7]
	global_load_dwordx4 v[42:45], v170, s[20:21] offset:16
	global_load_dwordx4 v[46:49], v170, s[20:21]
	global_load_dwordx4 v[34:37], v170, s[20:21] offset:528
	global_load_dwordx4 v[38:41], v170, s[20:21] offset:512
	global_load_dword v161, v[172:173], off
	v_add_u32_e32 v184, s13, v165
	v_ashrrev_i32_e32 v185, 31, v184
	v_lshl_add_u64 v[184:185], v[184:185], 2, s[6:7]
	global_load_dword v198, v[184:185], off
	v_add_u32_e32 v186, s13, v166
	v_ashrrev_i32_e32 v187, 31, v186
	v_lshl_add_u64 v[186:187], v[186:187], 2, s[6:7]
	global_load_dword v199, v[186:187], off
	v_add_u32_e32 v188, s13, v167
	v_ashrrev_i32_e32 v189, 31, v188
	v_lshl_add_u64 v[188:189], v[188:189], 2, s[6:7]
	global_load_dword v200, v[188:189], off
	v_add_u32_e32 v190, 0x80, v160
	v_ashrrev_i32_e32 v191, 31, v190
	v_lshl_add_u64 v[190:191], v[190:191], 2, s[6:7]
	global_load_dword v201, v[190:191], off
	v_add_u32_e32 v192, 0x90, v160
	v_ashrrev_i32_e32 v193, 31, v192
	v_lshl_add_u64 v[192:193], v[192:193], 2, s[6:7]
	global_load_dword v202, v[192:193], off
	v_add_u32_e32 v194, 0xa0, v160
	v_ashrrev_i32_e32 v195, 31, v194
	v_lshl_add_u64 v[194:195], v[194:195], 2, s[6:7]
	global_load_dword v203, v[194:195], off
	v_add_u32_e32 v196, 0xb0, v160
	v_ashrrev_i32_e32 v197, 31, v196
	v_lshl_add_u64 v[196:197], v[196:197], 2, s[6:7]
	global_load_dword v204, v[196:197], off
	s_mov_b32 s22, 0xbfb8aa3b
	v_lshl_or_b32 v162, s43, 7, v168
	v_ashrrev_i32_e32 v163, 31, v162
	s_movk_i32 s15, 0x1600
	s_andn2_b64 vcc, exec, s[0:1]
	v_readlane_b32 s49, v254, 28
	s_waitcnt vmcnt(7)
	v_fmamk_f32 v161, v161, 0x3a800000, v225
	v_rsq_f32_e32 v172, v161
	s_nop 0
	v_pk_fma_f32 v[142:143], v[142:143], v[172:173], v[46:47] op_sel_hi:[1,0,1]
	v_pk_fma_f32 v[144:145], v[144:145], v[172:173], v[48:49] op_sel_hi:[1,0,1]
	v_pk_fma_f32 v[140:141], v[140:141], v[172:173], v[44:45] op_sel_hi:[1,0,1]
	v_pk_fma_f32 v[138:139], v[138:139], v[172:173], v[42:43] op_sel_hi:[1,0,1]
	v_pk_mul_f32 v[176:177], v[142:143], s[22:23] op_sel_hi:[1,0]
	v_pk_mul_f32 v[174:175], v[144:145], s[22:23] op_sel_hi:[1,0]
	v_pk_mul_f32 v[178:179], v[140:141], s[22:23] op_sel_hi:[1,0]
	v_pk_mul_f32 v[180:181], v[138:139], s[22:23] op_sel_hi:[1,0]
	v_exp_f32_e32 v176, v176
	v_exp_f32_e32 v177, v177
	v_exp_f32_e32 v180, v180
	v_exp_f32_e32 v181, v181
	v_exp_f32_e32 v174, v174
	v_exp_f32_e32 v178, v178
	v_exp_f32_e32 v175, v175
	v_exp_f32_e32 v179, v179
	v_pk_add_f32 v[176:177], v[176:177], 1.0 op_sel_hi:[1,0]
	v_pk_add_f32 v[180:181], v[180:181], 1.0 op_sel_hi:[1,0]
	v_pk_add_f32 v[174:175], v[174:175], 1.0 op_sel_hi:[1,0]
	v_pk_add_f32 v[178:179], v[178:179], 1.0 op_sel_hi:[1,0]
	v_rcp_f32_e32 v176, v176
	v_rcp_f32_e32 v177, v177
	v_rcp_f32_e32 v180, v180
	v_rcp_f32_e32 v181, v181
	v_rcp_f32_e32 v174, v174
	v_rcp_f32_e32 v178, v178
	v_rcp_f32_e32 v175, v175
	v_rcp_f32_e32 v179, v179
	v_pk_fma_f32 v[134:135], v[134:135], v[172:173], v[38:39] op_sel_hi:[1,0,1]
	v_pk_fma_f32 v[136:137], v[136:137], v[172:173], v[40:41] op_sel_hi:[1,0,1]
	v_pk_fma_f32 v[132:133], v[132:133], v[172:173], v[36:37] op_sel_hi:[1,0,1]
	v_pk_fma_f32 v[130:131], v[130:131], v[172:173], v[34:35] op_sel_hi:[1,0,1]
	v_pk_mul_f32 v[134:135], v[142:143], v[134:135]
	v_pk_mul_f32 v[136:137], v[144:145], v[136:137]
	v_pk_mul_f32 v[134:135], v[134:135], v[176:177]
	v_pk_mul_f32 v[132:133], v[140:141], v[132:133]
	v_pk_mul_f32 v[130:131], v[138:139], v[130:131]
	v_pk_mul_f32 v[136:137], v[136:137], v[174:175]
	v_pk_mul_f32 v[138:139], v[132:133], v[178:179]
	v_pk_mul_f32 v[132:133], v[130:131], v[180:181]
	v_cvt_pk_bf16_f32 v130, v134, v135
	v_mov_b64_e32 v[134:135], s[8:9]
	v_cvt_pk_bf16_f32 v131, v136, v137
	v_cvt_pk_bf16_f32 v132, v132, v133
	v_cvt_pk_bf16_f32 v133, v138, v139
	v_mad_i64_i32 v[138:139], s[20:21], v160, s15, v[134:135]
	v_lshlrev_b64 v[136:137], 1, v[162:163]
	v_lshl_add_u64 v[138:139], v[138:139], 0, v[136:137]
	global_store_dwordx4 v[138:139], v[130:133], off
	s_nop 1
	v_add_u32_e32 v130, s13, v165
	s_waitcnt vmcnt(7)
	v_fmamk_f32 v131, v198, 0x3a800000, v225
	v_rsq_f32_e32 v132, v131
	s_nop 0
	v_pk_fma_f32 v[126:127], v[126:127], v[132:133], v[46:47] op_sel_hi:[1,0,1]
	v_pk_fma_f32 v[128:129], v[128:129], v[132:133], v[48:49] op_sel_hi:[1,0,1]
	v_pk_fma_f32 v[124:125], v[124:125], v[132:133], v[44:45] op_sel_hi:[1,0,1]
	v_pk_fma_f32 v[122:123], v[122:123], v[132:133], v[42:43] op_sel_hi:[1,0,1]
	v_pk_mul_f32 v[140:141], v[126:127], s[22:23] op_sel_hi:[1,0]
	v_pk_mul_f32 v[138:139], v[128:129], s[22:23] op_sel_hi:[1,0]
	v_pk_mul_f32 v[142:143], v[124:125], s[22:23] op_sel_hi:[1,0]
	v_pk_mul_f32 v[144:145], v[122:123], s[22:23] op_sel_hi:[1,0]
	v_exp_f32_e32 v140, v140
	v_exp_f32_e32 v141, v141
	v_exp_f32_e32 v144, v144
	v_exp_f32_e32 v145, v145
	v_exp_f32_e32 v138, v138
	v_exp_f32_e32 v142, v142
	v_exp_f32_e32 v139, v139
	v_exp_f32_e32 v143, v143
	v_pk_add_f32 v[140:141], v[140:141], 1.0 op_sel_hi:[1,0]
	v_pk_add_f32 v[144:145], v[144:145], 1.0 op_sel_hi:[1,0]
	v_pk_add_f32 v[138:139], v[138:139], 1.0 op_sel_hi:[1,0]
	v_pk_add_f32 v[142:143], v[142:143], 1.0 op_sel_hi:[1,0]
	v_rcp_f32_e32 v140, v140
	v_rcp_f32_e32 v141, v141
	v_rcp_f32_e32 v144, v144
	v_rcp_f32_e32 v145, v145
	v_rcp_f32_e32 v138, v138
	v_rcp_f32_e32 v142, v142
	v_rcp_f32_e32 v139, v139
	v_rcp_f32_e32 v143, v143
	v_pk_fma_f32 v[118:119], v[118:119], v[132:133], v[38:39] op_sel_hi:[1,0,1]
	v_pk_fma_f32 v[120:121], v[120:121], v[132:133], v[40:41] op_sel_hi:[1,0,1]
	v_pk_fma_f32 v[116:117], v[116:117], v[132:133], v[36:37] op_sel_hi:[1,0,1]
	v_pk_fma_f32 v[114:115], v[114:115], v[132:133], v[34:35] op_sel_hi:[1,0,1]
	v_pk_mul_f32 v[118:119], v[126:127], v[118:119]
	v_pk_mul_f32 v[120:121], v[128:129], v[120:121]
	v_pk_mul_f32 v[118:119], v[118:119], v[140:141]
	v_pk_mul_f32 v[116:117], v[124:125], v[116:117]
	v_pk_mul_f32 v[114:115], v[122:123], v[114:115]
	v_pk_mul_f32 v[120:121], v[120:121], v[138:139]
	v_pk_mul_f32 v[122:123], v[116:117], v[142:143]
	v_pk_mul_f32 v[116:117], v[114:115], v[144:145]
	v_cvt_pk_bf16_f32 v114, v118, v119
	v_mad_i64_i32 v[118:119], s[20:21], v130, s15, v[134:135]
	v_cvt_pk_bf16_f32 v115, v120, v121
	v_cvt_pk_bf16_f32 v116, v116, v117
	v_cvt_pk_bf16_f32 v117, v122, v123
	v_lshl_add_u64 v[118:119], v[118:119], 0, v[136:137]
	global_store_dwordx4 v[118:119], v[114:117], off
	s_nop 1
	v_add_u32_e32 v114, s13, v166
	s_waitcnt vmcnt(7)
	v_fmamk_f32 v115, v199, 0x3a800000, v225
	v_rsq_f32_e32 v116, v115
	s_nop 0
	v_pk_fma_f32 v[110:111], v[110:111], v[116:117], v[46:47] op_sel_hi:[1,0,1]
	v_pk_fma_f32 v[112:113], v[112:113], v[116:117], v[48:49] op_sel_hi:[1,0,1]
	v_pk_fma_f32 v[108:109], v[108:109], v[116:117], v[44:45] op_sel_hi:[1,0,1]
	v_pk_fma_f32 v[106:107], v[106:107], v[116:117], v[42:43] op_sel_hi:[1,0,1]
	v_pk_mul_f32 v[120:121], v[110:111], s[22:23] op_sel_hi:[1,0]
	v_pk_mul_f32 v[118:119], v[112:113], s[22:23] op_sel_hi:[1,0]
	v_pk_mul_f32 v[122:123], v[108:109], s[22:23] op_sel_hi:[1,0]
	v_pk_mul_f32 v[124:125], v[106:107], s[22:23] op_sel_hi:[1,0]
	v_exp_f32_e32 v120, v120
	v_exp_f32_e32 v121, v121
	v_exp_f32_e32 v124, v124
	v_exp_f32_e32 v125, v125
	v_exp_f32_e32 v118, v118
	v_exp_f32_e32 v122, v122
	v_exp_f32_e32 v119, v119
	v_exp_f32_e32 v123, v123
	v_pk_add_f32 v[120:121], v[120:121], 1.0 op_sel_hi:[1,0]
	v_pk_add_f32 v[124:125], v[124:125], 1.0 op_sel_hi:[1,0]
	v_pk_add_f32 v[118:119], v[118:119], 1.0 op_sel_hi:[1,0]
	v_pk_add_f32 v[122:123], v[122:123], 1.0 op_sel_hi:[1,0]
	v_rcp_f32_e32 v120, v120
	v_rcp_f32_e32 v121, v121
	v_rcp_f32_e32 v124, v124
	v_rcp_f32_e32 v125, v125
	v_rcp_f32_e32 v118, v118
	v_rcp_f32_e32 v122, v122
	v_rcp_f32_e32 v119, v119
	v_rcp_f32_e32 v123, v123
	v_pk_fma_f32 v[102:103], v[102:103], v[116:117], v[38:39] op_sel_hi:[1,0,1]
	v_pk_fma_f32 v[104:105], v[104:105], v[116:117], v[40:41] op_sel_hi:[1,0,1]
	v_pk_fma_f32 v[100:101], v[100:101], v[116:117], v[36:37] op_sel_hi:[1,0,1]
	v_pk_fma_f32 v[98:99], v[98:99], v[116:117], v[34:35] op_sel_hi:[1,0,1]
	v_pk_mul_f32 v[102:103], v[110:111], v[102:103]
	v_pk_mul_f32 v[104:105], v[112:113], v[104:105]
	v_pk_mul_f32 v[102:103], v[102:103], v[120:121]
	v_pk_mul_f32 v[100:101], v[108:109], v[100:101]
	v_pk_mul_f32 v[98:99], v[106:107], v[98:99]
	v_pk_mul_f32 v[104:105], v[104:105], v[118:119]
	v_pk_mul_f32 v[106:107], v[100:101], v[122:123]
	v_pk_mul_f32 v[100:101], v[98:99], v[124:125]
	v_cvt_pk_bf16_f32 v98, v102, v103
	v_mad_i64_i32 v[102:103], s[20:21], v114, s15, v[134:135]
	v_cvt_pk_bf16_f32 v99, v104, v105
	v_cvt_pk_bf16_f32 v100, v100, v101
	v_cvt_pk_bf16_f32 v101, v106, v107
	v_lshl_add_u64 v[102:103], v[102:103], 0, v[136:137]
	global_store_dwordx4 v[102:103], v[98:101], off
	s_nop 1
	v_add_u32_e32 v98, s13, v167
	s_waitcnt vmcnt(7)
	v_fmamk_f32 v99, v200, 0x3a800000, v225
	v_rsq_f32_e32 v100, v99
	s_nop 0
	v_pk_fma_f32 v[94:95], v[94:95], v[100:101], v[46:47] op_sel_hi:[1,0,1]
	v_pk_fma_f32 v[96:97], v[96:97], v[100:101], v[48:49] op_sel_hi:[1,0,1]
	v_pk_fma_f32 v[92:93], v[92:93], v[100:101], v[44:45] op_sel_hi:[1,0,1]
	v_pk_fma_f32 v[90:91], v[90:91], v[100:101], v[42:43] op_sel_hi:[1,0,1]
	v_pk_mul_f32 v[104:105], v[94:95], s[22:23] op_sel_hi:[1,0]
	v_pk_mul_f32 v[102:103], v[96:97], s[22:23] op_sel_hi:[1,0]
	v_pk_mul_f32 v[106:107], v[92:93], s[22:23] op_sel_hi:[1,0]
	v_pk_mul_f32 v[108:109], v[90:91], s[22:23] op_sel_hi:[1,0]
	v_exp_f32_e32 v104, v104
	v_exp_f32_e32 v105, v105
	v_exp_f32_e32 v108, v108
	v_exp_f32_e32 v109, v109
	v_exp_f32_e32 v102, v102
	v_exp_f32_e32 v106, v106
	v_exp_f32_e32 v103, v103
	v_exp_f32_e32 v107, v107
	v_pk_add_f32 v[104:105], v[104:105], 1.0 op_sel_hi:[1,0]
	v_pk_add_f32 v[108:109], v[108:109], 1.0 op_sel_hi:[1,0]
	v_pk_add_f32 v[102:103], v[102:103], 1.0 op_sel_hi:[1,0]
	v_pk_add_f32 v[106:107], v[106:107], 1.0 op_sel_hi:[1,0]
	v_rcp_f32_e32 v104, v104
	v_rcp_f32_e32 v105, v105
	v_rcp_f32_e32 v108, v108
	v_rcp_f32_e32 v109, v109
	v_rcp_f32_e32 v102, v102
	v_rcp_f32_e32 v106, v106
	v_rcp_f32_e32 v103, v103
	v_rcp_f32_e32 v107, v107
	v_pk_fma_f32 v[86:87], v[86:87], v[100:101], v[38:39] op_sel_hi:[1,0,1]
	v_pk_fma_f32 v[88:89], v[88:89], v[100:101], v[40:41] op_sel_hi:[1,0,1]
	v_pk_fma_f32 v[84:85], v[84:85], v[100:101], v[36:37] op_sel_hi:[1,0,1]
	v_pk_fma_f32 v[82:83], v[82:83], v[100:101], v[34:35] op_sel_hi:[1,0,1]
	v_pk_mul_f32 v[86:87], v[94:95], v[86:87]
	v_pk_mul_f32 v[88:89], v[96:97], v[88:89]
	v_pk_mul_f32 v[86:87], v[86:87], v[104:105]
	v_pk_mul_f32 v[84:85], v[92:93], v[84:85]
	v_pk_mul_f32 v[82:83], v[90:91], v[82:83]
	v_pk_mul_f32 v[88:89], v[88:89], v[102:103]
	v_pk_mul_f32 v[90:91], v[84:85], v[106:107]
	v_pk_mul_f32 v[84:85], v[82:83], v[108:109]
	v_cvt_pk_bf16_f32 v82, v86, v87
	v_mad_i64_i32 v[86:87], s[20:21], v98, s15, v[134:135]
	v_cvt_pk_bf16_f32 v83, v88, v89
	v_cvt_pk_bf16_f32 v84, v84, v85
	v_cvt_pk_bf16_f32 v85, v90, v91
	v_lshl_add_u64 v[86:87], v[86:87], 0, v[136:137]
	global_store_dwordx4 v[86:87], v[82:85], off
	s_nop 1
	v_add_u32_e32 v82, 0x80, v160
	s_waitcnt vmcnt(7)
	v_fmamk_f32 v83, v201, 0x3a800000, v225
	v_rsq_f32_e32 v84, v83
	s_nop 0
	v_pk_fma_f32 v[78:79], v[78:79], v[84:85], v[46:47] op_sel_hi:[1,0,1]
	v_pk_fma_f32 v[80:81], v[80:81], v[84:85], v[48:49] op_sel_hi:[1,0,1]
	v_pk_fma_f32 v[76:77], v[76:77], v[84:85], v[44:45] op_sel_hi:[1,0,1]
	v_pk_fma_f32 v[74:75], v[74:75], v[84:85], v[42:43] op_sel_hi:[1,0,1]
	v_pk_mul_f32 v[88:89], v[78:79], s[22:23] op_sel_hi:[1,0]
	v_pk_mul_f32 v[86:87], v[80:81], s[22:23] op_sel_hi:[1,0]
	v_pk_mul_f32 v[90:91], v[76:77], s[22:23] op_sel_hi:[1,0]
	v_pk_mul_f32 v[92:93], v[74:75], s[22:23] op_sel_hi:[1,0]
	v_exp_f32_e32 v88, v88
	v_exp_f32_e32 v89, v89
	v_exp_f32_e32 v92, v92
	v_exp_f32_e32 v93, v93
	v_exp_f32_e32 v86, v86
	v_exp_f32_e32 v90, v90
	v_exp_f32_e32 v87, v87
	v_exp_f32_e32 v91, v91
	v_pk_add_f32 v[88:89], v[88:89], 1.0 op_sel_hi:[1,0]
	v_pk_add_f32 v[92:93], v[92:93], 1.0 op_sel_hi:[1,0]
	v_pk_add_f32 v[86:87], v[86:87], 1.0 op_sel_hi:[1,0]
	v_pk_add_f32 v[90:91], v[90:91], 1.0 op_sel_hi:[1,0]
	v_rcp_f32_e32 v88, v88
	v_rcp_f32_e32 v89, v89
	v_rcp_f32_e32 v92, v92
	v_rcp_f32_e32 v93, v93
	v_rcp_f32_e32 v86, v86
	v_rcp_f32_e32 v90, v90
	v_rcp_f32_e32 v87, v87
	v_rcp_f32_e32 v91, v91
	v_pk_fma_f32 v[70:71], v[70:71], v[84:85], v[38:39] op_sel_hi:[1,0,1]
	v_pk_fma_f32 v[72:73], v[72:73], v[84:85], v[40:41] op_sel_hi:[1,0,1]
	v_pk_fma_f32 v[68:69], v[68:69], v[84:85], v[36:37] op_sel_hi:[1,0,1]
	v_pk_fma_f32 v[66:67], v[66:67], v[84:85], v[34:35] op_sel_hi:[1,0,1]
	v_pk_mul_f32 v[70:71], v[78:79], v[70:71]
	v_pk_mul_f32 v[72:73], v[80:81], v[72:73]
	v_pk_mul_f32 v[70:71], v[70:71], v[88:89]
	v_pk_mul_f32 v[68:69], v[76:77], v[68:69]
	v_pk_mul_f32 v[66:67], v[74:75], v[66:67]
	v_pk_mul_f32 v[72:73], v[72:73], v[86:87]
	v_pk_mul_f32 v[74:75], v[68:69], v[90:91]
	v_pk_mul_f32 v[68:69], v[66:67], v[92:93]
	v_cvt_pk_bf16_f32 v66, v70, v71
	v_mad_i64_i32 v[70:71], s[20:21], v82, s15, v[134:135]
	v_cvt_pk_bf16_f32 v67, v72, v73
	v_cvt_pk_bf16_f32 v68, v68, v69
	v_cvt_pk_bf16_f32 v69, v74, v75
	v_lshl_add_u64 v[70:71], v[70:71], 0, v[136:137]
	global_store_dwordx4 v[70:71], v[66:69], off
	s_nop 1
	v_add_u32_e32 v66, 0x90, v160
	s_waitcnt vmcnt(7)
	v_fmamk_f32 v67, v202, 0x3a800000, v225
	v_rsq_f32_e32 v68, v67
	s_nop 0
	v_pk_fma_f32 v[62:63], v[62:63], v[68:69], v[46:47] op_sel_hi:[1,0,1]
	v_pk_fma_f32 v[64:65], v[64:65], v[68:69], v[48:49] op_sel_hi:[1,0,1]
	v_pk_fma_f32 v[60:61], v[60:61], v[68:69], v[44:45] op_sel_hi:[1,0,1]
	v_pk_fma_f32 v[58:59], v[58:59], v[68:69], v[42:43] op_sel_hi:[1,0,1]
	v_pk_mul_f32 v[72:73], v[62:63], s[22:23] op_sel_hi:[1,0]
	v_pk_mul_f32 v[70:71], v[64:65], s[22:23] op_sel_hi:[1,0]
	v_pk_mul_f32 v[74:75], v[60:61], s[22:23] op_sel_hi:[1,0]
	v_pk_mul_f32 v[76:77], v[58:59], s[22:23] op_sel_hi:[1,0]
	v_exp_f32_e32 v72, v72
	v_exp_f32_e32 v73, v73
	v_exp_f32_e32 v76, v76
	v_exp_f32_e32 v77, v77
	v_exp_f32_e32 v70, v70
	v_exp_f32_e32 v74, v74
	v_exp_f32_e32 v71, v71
	v_exp_f32_e32 v75, v75
	v_pk_add_f32 v[72:73], v[72:73], 1.0 op_sel_hi:[1,0]
	v_pk_add_f32 v[76:77], v[76:77], 1.0 op_sel_hi:[1,0]
	v_pk_add_f32 v[70:71], v[70:71], 1.0 op_sel_hi:[1,0]
	v_pk_add_f32 v[74:75], v[74:75], 1.0 op_sel_hi:[1,0]
	v_rcp_f32_e32 v72, v72
	v_rcp_f32_e32 v73, v73
	v_rcp_f32_e32 v76, v76
	v_rcp_f32_e32 v77, v77
	v_rcp_f32_e32 v70, v70
	v_rcp_f32_e32 v74, v74
	v_rcp_f32_e32 v71, v71
	v_rcp_f32_e32 v75, v75
	v_pk_fma_f32 v[54:55], v[54:55], v[68:69], v[38:39] op_sel_hi:[1,0,1]
	v_pk_fma_f32 v[56:57], v[56:57], v[68:69], v[40:41] op_sel_hi:[1,0,1]
	v_pk_fma_f32 v[52:53], v[52:53], v[68:69], v[36:37] op_sel_hi:[1,0,1]
	v_pk_fma_f32 v[50:51], v[50:51], v[68:69], v[34:35] op_sel_hi:[1,0,1]
	v_pk_mul_f32 v[54:55], v[62:63], v[54:55]
	v_pk_mul_f32 v[56:57], v[64:65], v[56:57]
	v_pk_mul_f32 v[54:55], v[54:55], v[72:73]
	v_pk_mul_f32 v[52:53], v[60:61], v[52:53]
	v_pk_mul_f32 v[50:51], v[58:59], v[50:51]
	v_pk_mul_f32 v[56:57], v[56:57], v[70:71]
	v_pk_mul_f32 v[58:59], v[52:53], v[74:75]
	v_pk_mul_f32 v[52:53], v[50:51], v[76:77]
	v_cvt_pk_bf16_f32 v50, v54, v55
	v_mad_i64_i32 v[54:55], s[20:21], v66, s15, v[134:135]
	v_cvt_pk_bf16_f32 v51, v56, v57
	v_cvt_pk_bf16_f32 v52, v52, v53
	v_cvt_pk_bf16_f32 v53, v58, v59
	v_lshl_add_u64 v[54:55], v[54:55], 0, v[136:137]
	global_store_dwordx4 v[54:55], v[50:53], off
	s_nop 1
	v_add_u32_e32 v50, 0xa0, v160
	s_waitcnt vmcnt(7)
	v_fmamk_f32 v51, v203, 0x3a800000, v225
	v_rsq_f32_e32 v52, v51
	s_nop 0
	v_pk_fma_f32 v[30:31], v[30:31], v[52:53], v[46:47] op_sel_hi:[1,0,1]
	v_pk_fma_f32 v[32:33], v[32:33], v[52:53], v[48:49] op_sel_hi:[1,0,1]
	v_pk_fma_f32 v[28:29], v[28:29], v[52:53], v[44:45] op_sel_hi:[1,0,1]
	v_pk_fma_f32 v[26:27], v[26:27], v[52:53], v[42:43] op_sel_hi:[1,0,1]
	v_pk_mul_f32 v[56:57], v[30:31], s[22:23] op_sel_hi:[1,0]
	v_pk_mul_f32 v[54:55], v[32:33], s[22:23] op_sel_hi:[1,0]
	v_pk_mul_f32 v[58:59], v[28:29], s[22:23] op_sel_hi:[1,0]
	v_pk_mul_f32 v[60:61], v[26:27], s[22:23] op_sel_hi:[1,0]
	v_exp_f32_e32 v56, v56
	v_exp_f32_e32 v57, v57
	v_exp_f32_e32 v60, v60
	v_exp_f32_e32 v61, v61
	v_exp_f32_e32 v54, v54
	v_exp_f32_e32 v58, v58
	v_exp_f32_e32 v55, v55
	v_exp_f32_e32 v59, v59
	v_pk_add_f32 v[56:57], v[56:57], 1.0 op_sel_hi:[1,0]
	v_pk_add_f32 v[60:61], v[60:61], 1.0 op_sel_hi:[1,0]
	v_pk_add_f32 v[54:55], v[54:55], 1.0 op_sel_hi:[1,0]
	v_pk_add_f32 v[58:59], v[58:59], 1.0 op_sel_hi:[1,0]
	v_rcp_f32_e32 v56, v56
	v_rcp_f32_e32 v57, v57
	v_rcp_f32_e32 v60, v60
	v_rcp_f32_e32 v61, v61
	v_rcp_f32_e32 v54, v54
	v_rcp_f32_e32 v58, v58
	v_rcp_f32_e32 v55, v55
	v_rcp_f32_e32 v59, v59
	v_pk_fma_f32 v[22:23], v[22:23], v[52:53], v[38:39] op_sel_hi:[1,0,1]
	v_pk_fma_f32 v[24:25], v[24:25], v[52:53], v[40:41] op_sel_hi:[1,0,1]
	v_pk_fma_f32 v[20:21], v[20:21], v[52:53], v[36:37] op_sel_hi:[1,0,1]
	v_pk_fma_f32 v[18:19], v[18:19], v[52:53], v[34:35] op_sel_hi:[1,0,1]
	v_pk_mul_f32 v[22:23], v[30:31], v[22:23]
	v_pk_mul_f32 v[24:25], v[32:33], v[24:25]
	v_pk_mul_f32 v[22:23], v[22:23], v[56:57]
	v_pk_mul_f32 v[20:21], v[28:29], v[20:21]
	v_pk_mul_f32 v[18:19], v[26:27], v[18:19]
	v_pk_mul_f32 v[24:25], v[24:25], v[54:55]
	v_pk_mul_f32 v[26:27], v[20:21], v[58:59]
	v_pk_mul_f32 v[20:21], v[18:19], v[60:61]
	v_cvt_pk_bf16_f32 v18, v22, v23
	v_mad_i64_i32 v[22:23], s[20:21], v50, s15, v[134:135]
	v_cvt_pk_bf16_f32 v19, v24, v25
	v_cvt_pk_bf16_f32 v20, v20, v21
	v_cvt_pk_bf16_f32 v21, v26, v27
	v_lshl_add_u64 v[22:23], v[22:23], 0, v[136:137]
	global_store_dwordx4 v[22:23], v[18:21], off
	s_nop 1
	v_add_u32_e32 v18, 0xb0, v160
	s_waitcnt vmcnt(7)
	v_fmamk_f32 v19, v204, 0x3a800000, v225
	v_rsq_f32_e32 v20, v19
	s_nop 0
	v_pk_fma_f32 v[14:15], v[14:15], v[20:21], v[46:47] op_sel_hi:[1,0,1]
	v_pk_fma_f32 v[16:17], v[16:17], v[20:21], v[48:49] op_sel_hi:[1,0,1]
	v_pk_fma_f32 v[12:13], v[12:13], v[20:21], v[44:45] op_sel_hi:[1,0,1]
	v_pk_fma_f32 v[10:11], v[10:11], v[20:21], v[42:43] op_sel_hi:[1,0,1]
	v_pk_mul_f32 v[24:25], v[14:15], s[22:23] op_sel_hi:[1,0]
	v_pk_mul_f32 v[22:23], v[16:17], s[22:23] op_sel_hi:[1,0]
	v_pk_mul_f32 v[26:27], v[12:13], s[22:23] op_sel_hi:[1,0]
	v_pk_mul_f32 v[28:29], v[10:11], s[22:23] op_sel_hi:[1,0]
	v_exp_f32_e32 v24, v24
	v_exp_f32_e32 v25, v25
	v_exp_f32_e32 v28, v28
	v_exp_f32_e32 v29, v29
	v_exp_f32_e32 v22, v22
	v_exp_f32_e32 v26, v26
	v_exp_f32_e32 v23, v23
	v_exp_f32_e32 v27, v27
	v_pk_add_f32 v[24:25], v[24:25], 1.0 op_sel_hi:[1,0]
	v_pk_add_f32 v[28:29], v[28:29], 1.0 op_sel_hi:[1,0]
	v_pk_add_f32 v[22:23], v[22:23], 1.0 op_sel_hi:[1,0]
	v_pk_add_f32 v[26:27], v[26:27], 1.0 op_sel_hi:[1,0]
	v_rcp_f32_e32 v24, v24
	v_rcp_f32_e32 v25, v25
	v_rcp_f32_e32 v28, v28
	v_rcp_f32_e32 v29, v29
	v_rcp_f32_e32 v22, v22
	v_rcp_f32_e32 v26, v26
	v_rcp_f32_e32 v23, v23
	v_rcp_f32_e32 v27, v27
	v_pk_fma_f32 v[6:7], v[6:7], v[20:21], v[38:39] op_sel_hi:[1,0,1]
	v_pk_fma_f32 v[8:9], v[8:9], v[20:21], v[40:41] op_sel_hi:[1,0,1]
	v_pk_fma_f32 v[4:5], v[4:5], v[20:21], v[36:37] op_sel_hi:[1,0,1]
	v_pk_fma_f32 v[2:3], v[2:3], v[20:21], v[34:35] op_sel_hi:[1,0,1]
	v_pk_mul_f32 v[6:7], v[14:15], v[6:7]
	v_pk_mul_f32 v[8:9], v[16:17], v[8:9]
	v_pk_mul_f32 v[6:7], v[6:7], v[24:25]
	v_pk_mul_f32 v[4:5], v[12:13], v[4:5]
	v_pk_mul_f32 v[2:3], v[10:11], v[2:3]
	v_pk_mul_f32 v[8:9], v[8:9], v[22:23]
	v_pk_mul_f32 v[10:11], v[4:5], v[26:27]
	v_pk_mul_f32 v[4:5], v[2:3], v[28:29]
	v_cvt_pk_bf16_f32 v2, v6, v7
	v_mad_i64_i32 v[6:7], s[20:21], v18, s15, v[134:135]
	v_cvt_pk_bf16_f32 v3, v8, v9
	v_cvt_pk_bf16_f32 v4, v4, v5
	v_cvt_pk_bf16_f32 v5, v10, v11
	v_lshl_add_u64 v[6:7], v[6:7], 0, v[136:137]
	s_mov_b64 s[20:21], -1
	global_store_dwordx4 v[6:7], v[2:5], off
	s_cbranch_vccnz .LBB0_222
	s_andn2_b64 vcc, exec, s[4:5]
	s_cbranch_vccnz .LBB0_221
	s_barrier
	s_branch .LBB0_221

.LBB0_1488:
	s_min_i32 s15, s22, 64
	s_lshr_b32 s15, s15, 4
	s_mul_i32 s26, s15, 0x1600
	s_ashr_i32 s27, s26, 31
	s_lshl_b64 s[26:27], s[26:27], 2
	s_add_u32 s15, s43, s26
	s_addc_u32 s17, s44, s27
	s_lshl_b32 s26, s24, 8
	s_ashr_i32 s27, s26, 31
	s_lshl_b64 s[26:27], s[26:27], 2
	s_add_u32 s15, s15, s26
	s_addc_u32 s17, s17, s27
	s_add_u32 s26, s15, s49
	s_addc_u32 s27, s17, 0
	s_lshl_b32 s15, s22, 8
	v_add_u32_e32 v160, s15, v1
	v_ashrrev_i32_e32 v161, 31, v160
	v_lshl_add_u64 v[172:173], v[160:161], 2, s[4:5]
	global_load_dwordx4 v[42:45], v170, s[26:27] offset:16
	global_load_dwordx4 v[46:49], v170, s[26:27]
	global_load_dwordx4 v[34:37], v170, s[26:27] offset:528
	global_load_dwordx4 v[38:41], v170, s[26:27] offset:512
	global_load_dword v161, v[172:173], off
	v_add_u32_e32 v184, s15, v165
	v_ashrrev_i32_e32 v185, 31, v184
	v_lshl_add_u64 v[184:185], v[184:185], 2, s[4:5]
	global_load_dword v198, v[184:185], off
	v_add_u32_e32 v186, s15, v166
	v_ashrrev_i32_e32 v187, 31, v186
	v_lshl_add_u64 v[186:187], v[186:187], 2, s[4:5]
	global_load_dword v199, v[186:187], off
	v_add_u32_e32 v188, s15, v167
	v_ashrrev_i32_e32 v189, 31, v188
	v_lshl_add_u64 v[188:189], v[188:189], 2, s[4:5]
	global_load_dword v200, v[188:189], off
	v_add_u32_e32 v190, 0x80, v160
	v_ashrrev_i32_e32 v191, 31, v190
	v_lshl_add_u64 v[190:191], v[190:191], 2, s[4:5]
	global_load_dword v201, v[190:191], off
	v_add_u32_e32 v192, 0x90, v160
	v_ashrrev_i32_e32 v193, 31, v192
	v_lshl_add_u64 v[192:193], v[192:193], 2, s[4:5]
	global_load_dword v202, v[192:193], off
	v_add_u32_e32 v194, 0xa0, v160
	v_ashrrev_i32_e32 v195, 31, v194
	v_lshl_add_u64 v[194:195], v[194:195], 2, s[4:5]
	global_load_dword v203, v[194:195], off
	v_add_u32_e32 v196, 0xb0, v160
	v_ashrrev_i32_e32 v197, 31, v196
	v_lshl_add_u64 v[196:197], v[196:197], 2, s[4:5]
	global_load_dword v204, v[196:197], off
	v_lshl_or_b32 v162, s24, 7, v168
	s_mov_b32 s24, 0xbfb8aa3b
	v_ashrrev_i32_e32 v163, 31, v162
	s_movk_i32 s17, 0x1600
	v_readlane_b32 s54, v254, 16
	s_andn2_b64 vcc, exec, s[6:7]
	v_readlane_b32 s55, v254, 17
	s_movk_i32 s56, 0x3fff
	s_waitcnt vmcnt(7)
	v_fmamk_f32 v161, v161, 0x3a800000, v225
	v_rsq_f32_e32 v172, v161
	s_nop 0
	v_pk_fma_f32 v[142:143], v[142:143], v[172:173], v[46:47] op_sel_hi:[1,0,1]
	v_pk_fma_f32 v[144:145], v[144:145], v[172:173], v[48:49] op_sel_hi:[1,0,1]
	v_pk_fma_f32 v[140:141], v[140:141], v[172:173], v[44:45] op_sel_hi:[1,0,1]
	v_pk_fma_f32 v[138:139], v[138:139], v[172:173], v[42:43] op_sel_hi:[1,0,1]
	v_pk_mul_f32 v[176:177], v[142:143], s[24:25] op_sel_hi:[1,0]
	v_pk_mul_f32 v[174:175], v[144:145], s[24:25] op_sel_hi:[1,0]
	v_pk_mul_f32 v[178:179], v[140:141], s[24:25] op_sel_hi:[1,0]
	v_pk_mul_f32 v[180:181], v[138:139], s[24:25] op_sel_hi:[1,0]
	v_exp_f32_e32 v176, v176
	v_exp_f32_e32 v177, v177
	v_exp_f32_e32 v180, v180
	v_exp_f32_e32 v181, v181
	v_exp_f32_e32 v174, v174
	v_exp_f32_e32 v178, v178
	v_exp_f32_e32 v175, v175
	v_exp_f32_e32 v179, v179
	v_pk_add_f32 v[176:177], v[176:177], 1.0 op_sel_hi:[1,0]
	v_pk_add_f32 v[180:181], v[180:181], 1.0 op_sel_hi:[1,0]
	v_pk_add_f32 v[174:175], v[174:175], 1.0 op_sel_hi:[1,0]
	v_pk_add_f32 v[178:179], v[178:179], 1.0 op_sel_hi:[1,0]
	v_rcp_f32_e32 v176, v176
	v_rcp_f32_e32 v177, v177
	v_rcp_f32_e32 v180, v180
	v_rcp_f32_e32 v181, v181
	v_rcp_f32_e32 v174, v174
	v_rcp_f32_e32 v178, v178
	v_rcp_f32_e32 v175, v175
	v_rcp_f32_e32 v179, v179
	v_pk_fma_f32 v[134:135], v[134:135], v[172:173], v[38:39] op_sel_hi:[1,0,1]
	v_pk_fma_f32 v[136:137], v[136:137], v[172:173], v[40:41] op_sel_hi:[1,0,1]
	v_pk_fma_f32 v[132:133], v[132:133], v[172:173], v[36:37] op_sel_hi:[1,0,1]
	v_pk_fma_f32 v[130:131], v[130:131], v[172:173], v[34:35] op_sel_hi:[1,0,1]
	v_pk_mul_f32 v[134:135], v[142:143], v[134:135]
	v_pk_mul_f32 v[136:137], v[144:145], v[136:137]
	v_pk_mul_f32 v[134:135], v[134:135], v[176:177]
	v_pk_mul_f32 v[132:133], v[140:141], v[132:133]
	v_pk_mul_f32 v[130:131], v[138:139], v[130:131]
	v_pk_mul_f32 v[136:137], v[136:137], v[174:175]
	v_pk_mul_f32 v[138:139], v[132:133], v[178:179]
	v_pk_mul_f32 v[132:133], v[130:131], v[180:181]
	v_cvt_pk_bf16_f32 v130, v134, v135
	v_mov_b64_e32 v[134:135], s[8:9]
	v_cvt_pk_bf16_f32 v131, v136, v137
	v_cvt_pk_bf16_f32 v132, v132, v133
	v_cvt_pk_bf16_f32 v133, v138, v139
	v_mad_i64_i32 v[138:139], s[22:23], v160, s17, v[134:135]
	v_lshlrev_b64 v[136:137], 1, v[162:163]
	v_lshl_add_u64 v[138:139], v[138:139], 0, v[136:137]
	global_store_dwordx4 v[138:139], v[130:133], off
	s_nop 1
	v_add_u32_e32 v130, s15, v165
	s_waitcnt vmcnt(7)
	v_fmamk_f32 v131, v198, 0x3a800000, v225
	v_rsq_f32_e32 v132, v131
	s_nop 0
	v_pk_fma_f32 v[126:127], v[126:127], v[132:133], v[46:47] op_sel_hi:[1,0,1]
	v_pk_fma_f32 v[128:129], v[128:129], v[132:133], v[48:49] op_sel_hi:[1,0,1]
	v_pk_fma_f32 v[124:125], v[124:125], v[132:133], v[44:45] op_sel_hi:[1,0,1]
	v_pk_fma_f32 v[122:123], v[122:123], v[132:133], v[42:43] op_sel_hi:[1,0,1]
	v_pk_mul_f32 v[140:141], v[126:127], s[24:25] op_sel_hi:[1,0]
	v_pk_mul_f32 v[138:139], v[128:129], s[24:25] op_sel_hi:[1,0]
	v_pk_mul_f32 v[142:143], v[124:125], s[24:25] op_sel_hi:[1,0]
	v_pk_mul_f32 v[144:145], v[122:123], s[24:25] op_sel_hi:[1,0]
	v_exp_f32_e32 v140, v140
	v_exp_f32_e32 v141, v141
	v_exp_f32_e32 v144, v144
	v_exp_f32_e32 v145, v145
	v_exp_f32_e32 v138, v138
	v_exp_f32_e32 v142, v142
	v_exp_f32_e32 v139, v139
	v_exp_f32_e32 v143, v143
	v_pk_add_f32 v[140:141], v[140:141], 1.0 op_sel_hi:[1,0]
	v_pk_add_f32 v[144:145], v[144:145], 1.0 op_sel_hi:[1,0]
	v_pk_add_f32 v[138:139], v[138:139], 1.0 op_sel_hi:[1,0]
	v_pk_add_f32 v[142:143], v[142:143], 1.0 op_sel_hi:[1,0]
	v_rcp_f32_e32 v140, v140
	v_rcp_f32_e32 v141, v141
	v_rcp_f32_e32 v144, v144
	v_rcp_f32_e32 v145, v145
	v_rcp_f32_e32 v138, v138
	v_rcp_f32_e32 v142, v142
	v_rcp_f32_e32 v139, v139
	v_rcp_f32_e32 v143, v143
	v_pk_fma_f32 v[118:119], v[118:119], v[132:133], v[38:39] op_sel_hi:[1,0,1]
	v_pk_fma_f32 v[120:121], v[120:121], v[132:133], v[40:41] op_sel_hi:[1,0,1]
	v_pk_fma_f32 v[116:117], v[116:117], v[132:133], v[36:37] op_sel_hi:[1,0,1]
	v_pk_fma_f32 v[114:115], v[114:115], v[132:133], v[34:35] op_sel_hi:[1,0,1]
	v_pk_mul_f32 v[118:119], v[126:127], v[118:119]
	v_pk_mul_f32 v[120:121], v[128:129], v[120:121]
	v_pk_mul_f32 v[118:119], v[118:119], v[140:141]
	v_pk_mul_f32 v[116:117], v[124:125], v[116:117]
	v_pk_mul_f32 v[114:115], v[122:123], v[114:115]
	v_pk_mul_f32 v[120:121], v[120:121], v[138:139]
	v_pk_mul_f32 v[122:123], v[116:117], v[142:143]
	v_pk_mul_f32 v[116:117], v[114:115], v[144:145]
	v_cvt_pk_bf16_f32 v114, v118, v119
	v_mad_i64_i32 v[118:119], s[22:23], v130, s17, v[134:135]
	v_cvt_pk_bf16_f32 v115, v120, v121
	v_cvt_pk_bf16_f32 v116, v116, v117
	v_cvt_pk_bf16_f32 v117, v122, v123
	v_lshl_add_u64 v[118:119], v[118:119], 0, v[136:137]
	global_store_dwordx4 v[118:119], v[114:117], off
	s_nop 1
	v_add_u32_e32 v114, s15, v166
	s_waitcnt vmcnt(7)
	v_fmamk_f32 v115, v199, 0x3a800000, v225
	v_rsq_f32_e32 v116, v115
	s_nop 0
	v_pk_fma_f32 v[110:111], v[110:111], v[116:117], v[46:47] op_sel_hi:[1,0,1]
	v_pk_fma_f32 v[112:113], v[112:113], v[116:117], v[48:49] op_sel_hi:[1,0,1]
	v_pk_fma_f32 v[108:109], v[108:109], v[116:117], v[44:45] op_sel_hi:[1,0,1]
	v_pk_fma_f32 v[106:107], v[106:107], v[116:117], v[42:43] op_sel_hi:[1,0,1]
	v_pk_mul_f32 v[120:121], v[110:111], s[24:25] op_sel_hi:[1,0]
	v_pk_mul_f32 v[118:119], v[112:113], s[24:25] op_sel_hi:[1,0]
	v_pk_mul_f32 v[122:123], v[108:109], s[24:25] op_sel_hi:[1,0]
	v_pk_mul_f32 v[124:125], v[106:107], s[24:25] op_sel_hi:[1,0]
	v_exp_f32_e32 v120, v120
	v_exp_f32_e32 v121, v121
	v_exp_f32_e32 v124, v124
	v_exp_f32_e32 v125, v125
	v_exp_f32_e32 v118, v118
	v_exp_f32_e32 v122, v122
	v_exp_f32_e32 v119, v119
	v_exp_f32_e32 v123, v123
	v_pk_add_f32 v[120:121], v[120:121], 1.0 op_sel_hi:[1,0]
	v_pk_add_f32 v[124:125], v[124:125], 1.0 op_sel_hi:[1,0]
	v_pk_add_f32 v[118:119], v[118:119], 1.0 op_sel_hi:[1,0]
	v_pk_add_f32 v[122:123], v[122:123], 1.0 op_sel_hi:[1,0]
	v_rcp_f32_e32 v120, v120
	v_rcp_f32_e32 v121, v121
	v_rcp_f32_e32 v124, v124
	v_rcp_f32_e32 v125, v125
	v_rcp_f32_e32 v118, v118
	v_rcp_f32_e32 v122, v122
	v_rcp_f32_e32 v119, v119
	v_rcp_f32_e32 v123, v123
	v_pk_fma_f32 v[102:103], v[102:103], v[116:117], v[38:39] op_sel_hi:[1,0,1]
	v_pk_fma_f32 v[104:105], v[104:105], v[116:117], v[40:41] op_sel_hi:[1,0,1]
	v_pk_fma_f32 v[100:101], v[100:101], v[116:117], v[36:37] op_sel_hi:[1,0,1]
	v_pk_fma_f32 v[98:99], v[98:99], v[116:117], v[34:35] op_sel_hi:[1,0,1]
	v_pk_mul_f32 v[102:103], v[110:111], v[102:103]
	v_pk_mul_f32 v[104:105], v[112:113], v[104:105]
	v_pk_mul_f32 v[102:103], v[102:103], v[120:121]
	v_pk_mul_f32 v[100:101], v[108:109], v[100:101]
	v_pk_mul_f32 v[98:99], v[106:107], v[98:99]
	v_pk_mul_f32 v[104:105], v[104:105], v[118:119]
	v_pk_mul_f32 v[106:107], v[100:101], v[122:123]
	v_pk_mul_f32 v[100:101], v[98:99], v[124:125]
	v_cvt_pk_bf16_f32 v98, v102, v103
	v_mad_i64_i32 v[102:103], s[22:23], v114, s17, v[134:135]
	v_cvt_pk_bf16_f32 v99, v104, v105
	v_cvt_pk_bf16_f32 v100, v100, v101
	v_cvt_pk_bf16_f32 v101, v106, v107
	v_lshl_add_u64 v[102:103], v[102:103], 0, v[136:137]
	global_store_dwordx4 v[102:103], v[98:101], off
	s_nop 1
	v_add_u32_e32 v98, s15, v167
	s_waitcnt vmcnt(7)
	v_fmamk_f32 v99, v200, 0x3a800000, v225
	v_rsq_f32_e32 v100, v99
	s_nop 0
	v_pk_fma_f32 v[94:95], v[94:95], v[100:101], v[46:47] op_sel_hi:[1,0,1]
	v_pk_fma_f32 v[96:97], v[96:97], v[100:101], v[48:49] op_sel_hi:[1,0,1]
	v_pk_fma_f32 v[92:93], v[92:93], v[100:101], v[44:45] op_sel_hi:[1,0,1]
	v_pk_fma_f32 v[90:91], v[90:91], v[100:101], v[42:43] op_sel_hi:[1,0,1]
	v_pk_mul_f32 v[104:105], v[94:95], s[24:25] op_sel_hi:[1,0]
	v_pk_mul_f32 v[102:103], v[96:97], s[24:25] op_sel_hi:[1,0]
	v_pk_mul_f32 v[106:107], v[92:93], s[24:25] op_sel_hi:[1,0]
	v_pk_mul_f32 v[108:109], v[90:91], s[24:25] op_sel_hi:[1,0]
	v_exp_f32_e32 v104, v104
	v_exp_f32_e32 v105, v105
	v_exp_f32_e32 v108, v108
	v_exp_f32_e32 v109, v109
	v_exp_f32_e32 v102, v102
	v_exp_f32_e32 v106, v106
	v_exp_f32_e32 v103, v103
	v_exp_f32_e32 v107, v107
	v_pk_add_f32 v[104:105], v[104:105], 1.0 op_sel_hi:[1,0]
	v_pk_add_f32 v[108:109], v[108:109], 1.0 op_sel_hi:[1,0]
	v_pk_add_f32 v[102:103], v[102:103], 1.0 op_sel_hi:[1,0]
	v_pk_add_f32 v[106:107], v[106:107], 1.0 op_sel_hi:[1,0]
	v_rcp_f32_e32 v104, v104
	v_rcp_f32_e32 v105, v105
	v_rcp_f32_e32 v108, v108
	v_rcp_f32_e32 v109, v109
	v_rcp_f32_e32 v102, v102
	v_rcp_f32_e32 v106, v106
	v_rcp_f32_e32 v103, v103
	v_rcp_f32_e32 v107, v107
	v_pk_fma_f32 v[86:87], v[86:87], v[100:101], v[38:39] op_sel_hi:[1,0,1]
	v_pk_fma_f32 v[88:89], v[88:89], v[100:101], v[40:41] op_sel_hi:[1,0,1]
	v_pk_fma_f32 v[84:85], v[84:85], v[100:101], v[36:37] op_sel_hi:[1,0,1]
	v_pk_fma_f32 v[82:83], v[82:83], v[100:101], v[34:35] op_sel_hi:[1,0,1]
	v_pk_mul_f32 v[86:87], v[94:95], v[86:87]
	v_pk_mul_f32 v[88:89], v[96:97], v[88:89]
	v_pk_mul_f32 v[86:87], v[86:87], v[104:105]
	v_pk_mul_f32 v[84:85], v[92:93], v[84:85]
	v_pk_mul_f32 v[82:83], v[90:91], v[82:83]
	v_pk_mul_f32 v[88:89], v[88:89], v[102:103]
	v_pk_mul_f32 v[90:91], v[84:85], v[106:107]
	v_pk_mul_f32 v[84:85], v[82:83], v[108:109]
	v_cvt_pk_bf16_f32 v82, v86, v87
	v_mad_i64_i32 v[86:87], s[22:23], v98, s17, v[134:135]
	v_cvt_pk_bf16_f32 v83, v88, v89
	v_cvt_pk_bf16_f32 v84, v84, v85
	v_cvt_pk_bf16_f32 v85, v90, v91
	v_lshl_add_u64 v[86:87], v[86:87], 0, v[136:137]
	global_store_dwordx4 v[86:87], v[82:85], off
	s_nop 1
	v_add_u32_e32 v82, 0x80, v160
	s_waitcnt vmcnt(7)
	v_fmamk_f32 v83, v201, 0x3a800000, v225
	v_rsq_f32_e32 v84, v83
	s_nop 0
	v_pk_fma_f32 v[78:79], v[78:79], v[84:85], v[46:47] op_sel_hi:[1,0,1]
	v_pk_fma_f32 v[80:81], v[80:81], v[84:85], v[48:49] op_sel_hi:[1,0,1]
	v_pk_fma_f32 v[76:77], v[76:77], v[84:85], v[44:45] op_sel_hi:[1,0,1]
	v_pk_fma_f32 v[74:75], v[74:75], v[84:85], v[42:43] op_sel_hi:[1,0,1]
	v_pk_mul_f32 v[88:89], v[78:79], s[24:25] op_sel_hi:[1,0]
	v_pk_mul_f32 v[86:87], v[80:81], s[24:25] op_sel_hi:[1,0]
	v_pk_mul_f32 v[90:91], v[76:77], s[24:25] op_sel_hi:[1,0]
	v_pk_mul_f32 v[92:93], v[74:75], s[24:25] op_sel_hi:[1,0]
	v_exp_f32_e32 v88, v88
	v_exp_f32_e32 v89, v89
	v_exp_f32_e32 v92, v92
	v_exp_f32_e32 v93, v93
	v_exp_f32_e32 v86, v86
	v_exp_f32_e32 v90, v90
	v_exp_f32_e32 v87, v87
	v_exp_f32_e32 v91, v91
	v_pk_add_f32 v[88:89], v[88:89], 1.0 op_sel_hi:[1,0]
	v_pk_add_f32 v[92:93], v[92:93], 1.0 op_sel_hi:[1,0]
	v_pk_add_f32 v[86:87], v[86:87], 1.0 op_sel_hi:[1,0]
	v_pk_add_f32 v[90:91], v[90:91], 1.0 op_sel_hi:[1,0]
	v_rcp_f32_e32 v88, v88
	v_rcp_f32_e32 v89, v89
	v_rcp_f32_e32 v92, v92
	v_rcp_f32_e32 v93, v93
	v_rcp_f32_e32 v86, v86
	v_rcp_f32_e32 v90, v90
	v_rcp_f32_e32 v87, v87
	v_rcp_f32_e32 v91, v91
	v_pk_fma_f32 v[70:71], v[70:71], v[84:85], v[38:39] op_sel_hi:[1,0,1]
	v_pk_fma_f32 v[72:73], v[72:73], v[84:85], v[40:41] op_sel_hi:[1,0,1]
	v_pk_fma_f32 v[68:69], v[68:69], v[84:85], v[36:37] op_sel_hi:[1,0,1]
	v_pk_fma_f32 v[66:67], v[66:67], v[84:85], v[34:35] op_sel_hi:[1,0,1]
	v_pk_mul_f32 v[70:71], v[78:79], v[70:71]
	v_pk_mul_f32 v[72:73], v[80:81], v[72:73]
	v_pk_mul_f32 v[70:71], v[70:71], v[88:89]
	v_pk_mul_f32 v[68:69], v[76:77], v[68:69]
	v_pk_mul_f32 v[66:67], v[74:75], v[66:67]
	v_pk_mul_f32 v[72:73], v[72:73], v[86:87]
	v_pk_mul_f32 v[74:75], v[68:69], v[90:91]
	v_pk_mul_f32 v[68:69], v[66:67], v[92:93]
	v_cvt_pk_bf16_f32 v66, v70, v71
	v_mad_i64_i32 v[70:71], s[22:23], v82, s17, v[134:135]
	v_cvt_pk_bf16_f32 v67, v72, v73
	v_cvt_pk_bf16_f32 v68, v68, v69
	v_cvt_pk_bf16_f32 v69, v74, v75
	v_lshl_add_u64 v[70:71], v[70:71], 0, v[136:137]
	global_store_dwordx4 v[70:71], v[66:69], off
	s_nop 1
	v_add_u32_e32 v66, 0x90, v160
	s_waitcnt vmcnt(7)
	v_fmamk_f32 v67, v202, 0x3a800000, v225
	v_rsq_f32_e32 v68, v67
	s_nop 0
	v_pk_fma_f32 v[62:63], v[62:63], v[68:69], v[46:47] op_sel_hi:[1,0,1]
	v_pk_fma_f32 v[64:65], v[64:65], v[68:69], v[48:49] op_sel_hi:[1,0,1]
	v_pk_fma_f32 v[60:61], v[60:61], v[68:69], v[44:45] op_sel_hi:[1,0,1]
	v_pk_fma_f32 v[58:59], v[58:59], v[68:69], v[42:43] op_sel_hi:[1,0,1]
	v_pk_mul_f32 v[72:73], v[62:63], s[24:25] op_sel_hi:[1,0]
	v_pk_mul_f32 v[70:71], v[64:65], s[24:25] op_sel_hi:[1,0]
	v_pk_mul_f32 v[74:75], v[60:61], s[24:25] op_sel_hi:[1,0]
	v_pk_mul_f32 v[76:77], v[58:59], s[24:25] op_sel_hi:[1,0]
	v_exp_f32_e32 v72, v72
	v_exp_f32_e32 v73, v73
	v_exp_f32_e32 v76, v76
	v_exp_f32_e32 v77, v77
	v_exp_f32_e32 v70, v70
	v_exp_f32_e32 v74, v74
	v_exp_f32_e32 v71, v71
	v_exp_f32_e32 v75, v75
	v_pk_add_f32 v[72:73], v[72:73], 1.0 op_sel_hi:[1,0]
	v_pk_add_f32 v[76:77], v[76:77], 1.0 op_sel_hi:[1,0]
	v_pk_add_f32 v[70:71], v[70:71], 1.0 op_sel_hi:[1,0]
	v_pk_add_f32 v[74:75], v[74:75], 1.0 op_sel_hi:[1,0]
	v_rcp_f32_e32 v72, v72
	v_rcp_f32_e32 v73, v73
	v_rcp_f32_e32 v76, v76
	v_rcp_f32_e32 v77, v77
	v_rcp_f32_e32 v70, v70
	v_rcp_f32_e32 v74, v74
	v_rcp_f32_e32 v71, v71
	v_rcp_f32_e32 v75, v75
	v_pk_fma_f32 v[54:55], v[54:55], v[68:69], v[38:39] op_sel_hi:[1,0,1]
	v_pk_fma_f32 v[56:57], v[56:57], v[68:69], v[40:41] op_sel_hi:[1,0,1]
	v_pk_fma_f32 v[52:53], v[52:53], v[68:69], v[36:37] op_sel_hi:[1,0,1]
	v_pk_fma_f32 v[50:51], v[50:51], v[68:69], v[34:35] op_sel_hi:[1,0,1]
	v_pk_mul_f32 v[54:55], v[62:63], v[54:55]
	v_pk_mul_f32 v[56:57], v[64:65], v[56:57]
	v_pk_mul_f32 v[54:55], v[54:55], v[72:73]
	v_pk_mul_f32 v[52:53], v[60:61], v[52:53]
	v_pk_mul_f32 v[50:51], v[58:59], v[50:51]
	v_pk_mul_f32 v[56:57], v[56:57], v[70:71]
	v_pk_mul_f32 v[58:59], v[52:53], v[74:75]
	v_pk_mul_f32 v[52:53], v[50:51], v[76:77]
	v_cvt_pk_bf16_f32 v50, v54, v55
	v_mad_i64_i32 v[54:55], s[22:23], v66, s17, v[134:135]
	v_cvt_pk_bf16_f32 v51, v56, v57
	v_cvt_pk_bf16_f32 v52, v52, v53
	v_cvt_pk_bf16_f32 v53, v58, v59
	v_lshl_add_u64 v[54:55], v[54:55], 0, v[136:137]
	global_store_dwordx4 v[54:55], v[50:53], off
	s_nop 1
	v_add_u32_e32 v50, 0xa0, v160
	s_waitcnt vmcnt(7)
	v_fmamk_f32 v51, v203, 0x3a800000, v225
	v_rsq_f32_e32 v52, v51
	s_nop 0
	v_pk_fma_f32 v[30:31], v[30:31], v[52:53], v[46:47] op_sel_hi:[1,0,1]
	v_pk_fma_f32 v[32:33], v[32:33], v[52:53], v[48:49] op_sel_hi:[1,0,1]
	v_pk_fma_f32 v[28:29], v[28:29], v[52:53], v[44:45] op_sel_hi:[1,0,1]
	v_pk_fma_f32 v[26:27], v[26:27], v[52:53], v[42:43] op_sel_hi:[1,0,1]
	v_pk_mul_f32 v[56:57], v[30:31], s[24:25] op_sel_hi:[1,0]
	v_pk_mul_f32 v[54:55], v[32:33], s[24:25] op_sel_hi:[1,0]
	v_pk_mul_f32 v[58:59], v[28:29], s[24:25] op_sel_hi:[1,0]
	v_pk_mul_f32 v[60:61], v[26:27], s[24:25] op_sel_hi:[1,0]
	v_exp_f32_e32 v56, v56
	v_exp_f32_e32 v57, v57
	v_exp_f32_e32 v60, v60
	v_exp_f32_e32 v61, v61
	v_exp_f32_e32 v54, v54
	v_exp_f32_e32 v58, v58
	v_exp_f32_e32 v55, v55
	v_exp_f32_e32 v59, v59
	v_pk_add_f32 v[56:57], v[56:57], 1.0 op_sel_hi:[1,0]
	v_pk_add_f32 v[60:61], v[60:61], 1.0 op_sel_hi:[1,0]
	v_pk_add_f32 v[54:55], v[54:55], 1.0 op_sel_hi:[1,0]
	v_pk_add_f32 v[58:59], v[58:59], 1.0 op_sel_hi:[1,0]
	v_rcp_f32_e32 v56, v56
	v_rcp_f32_e32 v57, v57
	v_rcp_f32_e32 v60, v60
	v_rcp_f32_e32 v61, v61
	v_rcp_f32_e32 v54, v54
	v_rcp_f32_e32 v58, v58
	v_rcp_f32_e32 v55, v55
	v_rcp_f32_e32 v59, v59
	v_pk_fma_f32 v[22:23], v[22:23], v[52:53], v[38:39] op_sel_hi:[1,0,1]
	v_pk_fma_f32 v[24:25], v[24:25], v[52:53], v[40:41] op_sel_hi:[1,0,1]
	v_pk_fma_f32 v[20:21], v[20:21], v[52:53], v[36:37] op_sel_hi:[1,0,1]
	v_pk_fma_f32 v[18:19], v[18:19], v[52:53], v[34:35] op_sel_hi:[1,0,1]
	v_pk_mul_f32 v[22:23], v[30:31], v[22:23]
	v_pk_mul_f32 v[24:25], v[32:33], v[24:25]
	v_pk_mul_f32 v[22:23], v[22:23], v[56:57]
	v_pk_mul_f32 v[20:21], v[28:29], v[20:21]
	v_pk_mul_f32 v[18:19], v[26:27], v[18:19]
	v_pk_mul_f32 v[24:25], v[24:25], v[54:55]
	v_pk_mul_f32 v[26:27], v[20:21], v[58:59]
	v_pk_mul_f32 v[20:21], v[18:19], v[60:61]
	v_cvt_pk_bf16_f32 v18, v22, v23
	v_mad_i64_i32 v[22:23], s[22:23], v50, s17, v[134:135]
	v_cvt_pk_bf16_f32 v19, v24, v25
	v_cvt_pk_bf16_f32 v20, v20, v21
	v_cvt_pk_bf16_f32 v21, v26, v27
	v_lshl_add_u64 v[22:23], v[22:23], 0, v[136:137]
	global_store_dwordx4 v[22:23], v[18:21], off
	s_nop 1
	v_add_u32_e32 v18, 0xb0, v160
	s_waitcnt vmcnt(7)
	v_fmamk_f32 v19, v204, 0x3a800000, v225
	v_rsq_f32_e32 v20, v19
	s_nop 0
	v_pk_fma_f32 v[14:15], v[14:15], v[20:21], v[46:47] op_sel_hi:[1,0,1]
	v_pk_fma_f32 v[16:17], v[16:17], v[20:21], v[48:49] op_sel_hi:[1,0,1]
	v_pk_fma_f32 v[12:13], v[12:13], v[20:21], v[44:45] op_sel_hi:[1,0,1]
	v_pk_fma_f32 v[10:11], v[10:11], v[20:21], v[42:43] op_sel_hi:[1,0,1]
	v_pk_mul_f32 v[24:25], v[14:15], s[24:25] op_sel_hi:[1,0]
	v_pk_mul_f32 v[22:23], v[16:17], s[24:25] op_sel_hi:[1,0]
	v_pk_mul_f32 v[26:27], v[12:13], s[24:25] op_sel_hi:[1,0]
	v_pk_mul_f32 v[28:29], v[10:11], s[24:25] op_sel_hi:[1,0]
	v_exp_f32_e32 v24, v24
	v_exp_f32_e32 v25, v25
	v_exp_f32_e32 v28, v28
	v_exp_f32_e32 v29, v29
	v_exp_f32_e32 v22, v22
	v_exp_f32_e32 v26, v26
	v_exp_f32_e32 v23, v23
	v_exp_f32_e32 v27, v27
	v_pk_add_f32 v[24:25], v[24:25], 1.0 op_sel_hi:[1,0]
	v_pk_add_f32 v[28:29], v[28:29], 1.0 op_sel_hi:[1,0]
	v_pk_add_f32 v[22:23], v[22:23], 1.0 op_sel_hi:[1,0]
	v_pk_add_f32 v[26:27], v[26:27], 1.0 op_sel_hi:[1,0]
	v_rcp_f32_e32 v24, v24
	v_rcp_f32_e32 v25, v25
	v_rcp_f32_e32 v28, v28
	v_rcp_f32_e32 v29, v29
	v_rcp_f32_e32 v22, v22
	v_rcp_f32_e32 v26, v26
	v_rcp_f32_e32 v23, v23
	v_rcp_f32_e32 v27, v27
	v_pk_fma_f32 v[6:7], v[6:7], v[20:21], v[38:39] op_sel_hi:[1,0,1]
	v_pk_fma_f32 v[8:9], v[8:9], v[20:21], v[40:41] op_sel_hi:[1,0,1]
	v_pk_fma_f32 v[4:5], v[4:5], v[20:21], v[36:37] op_sel_hi:[1,0,1]
	v_pk_fma_f32 v[2:3], v[2:3], v[20:21], v[34:35] op_sel_hi:[1,0,1]
	v_pk_mul_f32 v[6:7], v[14:15], v[6:7]
	v_pk_mul_f32 v[8:9], v[16:17], v[8:9]
	v_pk_mul_f32 v[6:7], v[6:7], v[24:25]
	v_pk_mul_f32 v[4:5], v[12:13], v[4:5]
	v_pk_mul_f32 v[2:3], v[10:11], v[2:3]
	v_pk_mul_f32 v[8:9], v[8:9], v[22:23]
	v_pk_mul_f32 v[10:11], v[4:5], v[26:27]
	v_pk_mul_f32 v[4:5], v[2:3], v[28:29]
	v_cvt_pk_bf16_f32 v2, v6, v7
	v_mad_i64_i32 v[6:7], s[22:23], v18, s17, v[134:135]
	v_cvt_pk_bf16_f32 v3, v8, v9
	v_cvt_pk_bf16_f32 v4, v4, v5
	v_cvt_pk_bf16_f32 v5, v10, v11
	v_lshl_add_u64 v[6:7], v[6:7], 0, v[136:137]
	s_mov_b64 s[22:23], -1
	global_store_dwordx4 v[6:7], v[2:5], off
	s_cbranch_vccnz .LBB0_1481
	s_andn2_b64 vcc, exec, s[0:1]
	s_cbranch_vccnz .LBB0_1480
	s_barrier
	s_branch .LBB0_1480
